# stack: decode per-head edits + exp interleave + Mamba sample-scan butterfly via DPP instead of ds_bpermute
# speedup vs baseline: 1.0077x; 1.0037x over previous
.LBB0_2448:
	s_waitcnt vmcnt(1)
	v_mul_f32_e32 v19, 0x3fb8aa3b, v18
	v_rndne_f32_e32 v20, v19
	s_mov_b32 s12, 0x3fb8aa3b
	v_sub_f32_e32 v21, v19, v20
	v_fma_f32 v19, v18, s12, -v19
	v_fmac_f32_e32 v19, 0x32a5705f, v18
	v_add_f32_e32 v19, v21, v19
	v_exp_f32_e32 v19, v19
	v_cvt_i32_f32_e32 v20, v20
	s_mov_b32 s12, 0xc2ce8ed0
	v_cmp_ngt_f32_e32 vcc, s12, v18
	s_mov_b32 s12, 0x42b17218
	v_ldexp_f32 v19, v19, v20
	s_bfe_i32 s9, s10, 0x80000
	v_cndmask_b32_e32 v19, 0, v19, vcc
	v_cmp_nlt_f32_e32 vcc, s12, v18
	s_lshl_b32 s12, s8, 3
	v_readlane_b32 s36, v252, 4
	s_bfe_u32 s9, s9, 0x3000c
	s_add_i32 s12, s12, 0x8000
	v_readlane_b32 s37, v252, 5
	s_add_i32 s9, s10, s9
	s_ashr_i32 s13, s12, 31
	v_readlane_b32 s38, v252, 6
	v_readlane_b32 s39, v252, 7
	v_readlane_b32 s40, v252, 8
	v_readlane_b32 s41, v252, 9
	s_mov_b64 s[16:17], s[36:37]
	s_sext_i32_i8 s9, s9
	s_add_u32 s27, s16, s14
	s_mov_b64 s[18:19], s[38:39]
	s_addc_u32 s28, s17, s15
	s_lshl_b32 s14, s8, 11
	s_lshl_b32 s9, s9, 4
	s_mov_b64 s[20:21], s[40:41]
	s_sub_i32 s14, s24, s14
	s_and_b32 s18, s9, 0xffffff80
	v_readlane_b32 s42, v252, 10
	v_readlane_b32 s43, v252, 11
	s_ashr_i32 s15, s14, 31
	s_ashr_i32 s19, s18, 31
	s_lshl_b64 s[20:21], s[12:13], 7
	s_add_u32 s16, s27, s20
	v_readlane_b32 s36, v253, 10
	s_addc_u32 s17, s28, s21
	s_mul_i32 s9, s12, 0x1800
	v_readlane_b32 s50, v253, 24
	global_load_dword v191, v163, s[16:17]
	s_mul_hi_i32 s16, s12, 0x1800
	v_readlane_b32 s51, v253, 25
	s_add_u32 s9, s50, s9
	s_addc_u32 s26, s51, s16
	s_lshl_b64 s[16:17], s[14:15], 1
	s_add_u32 s30, s9, s16
	s_addc_u32 s31, s26, s17
	s_lshl_b64 s[18:19], s[18:19], 1
	v_cndmask_b32_e32 v173, v165, v19, vcc
	v_lshl_add_u64 v[18:19], s[30:31], 0, v[170:171]
	s_add_u32 s30, s9, s18
	s_addc_u32 s31, s26, s19
	s_or_b32 s29, s20, 0x80
	global_load_ushort v189, v[18:19], off
	v_lshl_add_u64 v[18:19], s[30:31], 0, v[162:163]
	s_add_u32 s30, s27, s29
	s_addc_u32 s31, s28, s21
	v_lshl_add_u64 v[20:21], v[18:19], 0, s[0:1]
	v_add_co_u32_e32 v18, vcc, s4, v18
	s_add_u32 s29, s9, 0x1800
	s_nop 0
	v_addc_co_u32_e32 v19, vcc, 0, v19, vcc
	s_addc_u32 s33, s26, 0
	global_load_dwordx4 v[154:157], v[18:19], off
	global_load_dwordx4 v[150:153], v[20:21], off offset:16
	global_load_dwordx4 v[146:149], v[20:21], off offset:1040
	global_load_dwordx4 v[158:161], v[20:21], off offset:1024
	global_load_dword v187, v163, s[30:31]
	s_add_u32 s30, s29, s16
	s_addc_u32 s31, s33, s17
	v_lshl_add_u64 v[18:19], s[30:31], 0, v[170:171]
	s_add_u32 s30, s29, s18
	s_addc_u32 s31, s33, s19
	s_or_b32 s29, s20, 0x100
	global_load_ushort v188, v[18:19], off
	v_lshl_add_u64 v[18:19], s[30:31], 0, v[162:163]
	s_add_u32 s30, s27, s29
	s_addc_u32 s31, s28, s21
	v_lshl_add_u64 v[20:21], v[18:19], 0, s[0:1]
	v_add_co_u32_e32 v18, vcc, s4, v18
	s_add_u32 s29, s9, 0x3000
	s_nop 0
	v_addc_co_u32_e32 v19, vcc, 0, v19, vcc
	s_addc_u32 s33, s26, 0
	global_load_dwordx4 v[138:141], v[18:19], off
	global_load_dwordx4 v[134:137], v[20:21], off offset:16
	global_load_dwordx4 v[130:133], v[20:21], off offset:1040
	global_load_dwordx4 v[142:145], v[20:21], off offset:1024
	global_load_dword v185, v163, s[30:31]
	s_add_u32 s30, s29, s16
	s_addc_u32 s31, s33, s17
	v_lshl_add_u64 v[18:19], s[30:31], 0, v[170:171]
	s_add_u32 s30, s29, s18
	s_addc_u32 s31, s33, s19
	s_or_b32 s29, s20, 0x180
	global_load_ushort v186, v[18:19], off
	v_lshl_add_u64 v[18:19], s[30:31], 0, v[162:163]
	s_add_u32 s30, s27, s29
	s_addc_u32 s31, s28, s21
	v_lshl_add_u64 v[20:21], v[18:19], 0, s[0:1]
	v_add_co_u32_e32 v18, vcc, s4, v18
	s_add_u32 s29, s9, 0x4800
	s_nop 0
	v_addc_co_u32_e32 v19, vcc, 0, v19, vcc
	s_addc_u32 s33, s26, 0
	global_load_dwordx4 v[122:125], v[18:19], off
	global_load_dwordx4 v[118:121], v[20:21], off offset:16
	global_load_dwordx4 v[114:117], v[20:21], off offset:1040
	global_load_dwordx4 v[126:129], v[20:21], off offset:1024
	global_load_dword v183, v163, s[30:31]
	s_add_u32 s30, s29, s16
	s_addc_u32 s31, s33, s17
	v_lshl_add_u64 v[18:19], s[30:31], 0, v[170:171]
	s_add_u32 s30, s29, s18
	s_addc_u32 s31, s33, s19
	s_or_b32 s29, s20, 0x200
	global_load_ushort v184, v[18:19], off
	v_lshl_add_u64 v[18:19], s[30:31], 0, v[162:163]
	s_add_u32 s30, s27, s29
	s_addc_u32 s31, s28, s21
	v_lshl_add_u64 v[20:21], v[18:19], 0, s[0:1]
	v_add_co_u32_e32 v18, vcc, s4, v18
	s_add_u32 s29, s9, 0x6000
	s_nop 0
	v_addc_co_u32_e32 v19, vcc, 0, v19, vcc
	s_addc_u32 s33, s26, 0
	global_load_dwordx4 v[106:109], v[18:19], off
	global_load_dwordx4 v[98:101], v[20:21], off offset:16
	global_load_dwordx4 v[94:97], v[20:21], off offset:1040
	global_load_dwordx4 v[110:113], v[20:21], off offset:1024
	global_load_dword v181, v163, s[30:31]
	s_add_u32 s30, s29, s16
	s_addc_u32 s31, s33, s17
	v_lshl_add_u64 v[18:19], s[30:31], 0, v[170:171]
	s_add_u32 s30, s29, s18
	s_addc_u32 s31, s33, s19
	s_or_b32 s29, s20, 0x280
	global_load_ushort v182, v[18:19], off
	v_lshl_add_u64 v[18:19], s[30:31], 0, v[162:163]
	s_add_u32 s30, s27, s29
	s_addc_u32 s31, s28, s21
	v_lshl_add_u64 v[20:21], v[18:19], 0, s[0:1]
	v_add_co_u32_e32 v18, vcc, s4, v18
	s_add_u32 s29, s9, 0x7800
	s_nop 0
	v_addc_co_u32_e32 v19, vcc, 0, v19, vcc
	s_addc_u32 s33, s26, 0
	global_load_dwordx4 v[82:85], v[18:19], off
	global_load_dwordx4 v[70:73], v[20:21], off offset:16
	global_load_dwordx4 v[66:69], v[20:21], off offset:1040
	global_load_dwordx4 v[86:89], v[20:21], off offset:1024
	global_load_dword v179, v163, s[30:31]
	s_add_u32 s30, s29, s16
	s_addc_u32 s31, s33, s17
	v_lshl_add_u64 v[18:19], s[30:31], 0, v[170:171]
	s_add_u32 s30, s29, s18
	s_addc_u32 s31, s33, s19
	s_or_b32 s29, s20, 0x300
	global_load_ushort v180, v[18:19], off
	v_lshl_add_u64 v[18:19], s[30:31], 0, v[162:163]
	s_add_u32 s30, s27, s29
	s_addc_u32 s31, s28, s21
	v_lshl_add_u64 v[20:21], v[18:19], 0, s[0:1]
	v_add_co_u32_e32 v18, vcc, s4, v18
	s_add_u32 s29, s9, 0x9000
	s_nop 0
	v_addc_co_u32_e32 v19, vcc, 0, v19, vcc
	s_addc_u32 s33, s26, 0
	global_load_dwordx4 v[58:61], v[18:19], off
	global_load_dwordx4 v[50:53], v[20:21], off offset:16
	global_load_dwordx4 v[54:57], v[20:21], off offset:1040
	global_load_dwordx4 v[62:65], v[20:21], off offset:1024
	global_load_dword v177, v163, s[30:31]
	s_add_u32 s30, s29, s16
	s_addc_u32 s31, s33, s17
	v_lshl_add_u64 v[18:19], s[30:31], 0, v[170:171]
	s_add_u32 s30, s29, s18
	s_addc_u32 s31, s33, s19
	s_or_b32 s20, s20, 0x380
	global_load_ushort v178, v[18:19], off
	v_lshl_add_u64 v[18:19], s[30:31], 0, v[162:163]
	s_add_u32 s20, s27, s20
	v_lshl_add_u64 v[20:21], v[18:19], 0, s[0:1]
	v_add_co_u32_e32 v18, vcc, s4, v18
	s_addc_u32 s21, s28, s21
	s_nop 0
	v_addc_co_u32_e32 v19, vcc, 0, v19, vcc
	s_add_u32 s9, s9, 0xa800
	global_load_dwordx4 v[42:45], v[18:19], off
	global_load_dwordx4 v[34:37], v[20:21], off offset:16
	global_load_dwordx4 v[38:41], v[20:21], off offset:1040
	global_load_dwordx4 v[46:49], v[20:21], off offset:1024
	global_load_dword v175, v163, s[20:21]
	s_addc_u32 s20, s26, 0
	s_add_u32 s16, s9, s16
	s_addc_u32 s17, s20, s17
	v_lshl_add_u64 v[18:19], s[16:17], 0, v[170:171]
	s_add_u32 s16, s9, s18
	s_addc_u32 s17, s20, s19
	global_load_ushort v176, v[18:19], off
	v_lshl_add_u64 v[18:19], s[16:17], 0, v[162:163]
	v_lshl_add_u64 v[30:31], v[18:19], 0, s[0:1]
	v_add_co_u32_e32 v18, vcc, s4, v18
	s_waitcnt vmcnt(43)
	v_mul_f32_e32 v190, v191, v173
	v_addc_co_u32_e32 v19, vcc, 0, v19, vcc
	global_load_dwordx4 v[26:29], v[18:19], off
	global_load_dwordx4 v[22:25], v[30:31], off offset:16
	s_nop 0
	global_load_dwordx4 v[18:21], v[30:31], off offset:1040
	s_nop 0
	global_load_dwordx4 v[30:33], v[30:31], off offset:1024
	v_mul_f32_e32 v190, 0xbfb8aa3b, v190
	v_exp_f32_e32 v190, v190
	s_waitcnt vmcnt(46)
	v_lshlrev_b32_e32 v189, 16, v189
	v_mul_f32_e32 v192, v191, v189
	s_waitcnt vmcnt(45)
	v_lshlrev_b32_e32 v194, 16, v154
	v_and_b32_e32 v195, 0xffff0000, v154
	v_pk_mul_f32 v[194:195], v[192:193], v[194:195] op_sel_hi:[0,1]
	v_pk_fma_f32 v[102:103], v[102:103], v[190:191], v[194:195] op_sel_hi:[1,0,1]
	s_waitcnt vmcnt(42)
	v_lshlrev_b32_e32 v154, 16, v158
	v_mul_f32_e32 v154, v102, v154
	v_and_b32_e32 v158, 0xffff0000, v158
	v_fmac_f32_e32 v154, v103, v158
	v_add_f32_e32 v158, 0, v154
	v_lshlrev_b32_e32 v154, 16, v155
	v_and_b32_e32 v155, 0xffff0000, v155
	v_pk_mul_f32 v[154:155], v[192:193], v[154:155] op_sel_hi:[0,1]
	v_pk_fma_f32 v[104:105], v[104:105], v[190:191], v[154:155] op_sel_hi:[1,0,1]
	v_lshlrev_b32_e32 v154, 16, v159
	v_mul_f32_e32 v154, v104, v154
	v_and_b32_e32 v155, 0xffff0000, v159
	v_fmac_f32_e32 v154, v105, v155
	v_add_f32_e32 v158, v154, v158
	v_lshlrev_b32_e32 v154, 16, v156
	v_and_b32_e32 v155, 0xffff0000, v156
	v_pk_mul_f32 v[154:155], v[192:193], v[154:155] op_sel_hi:[0,1]
	v_pk_fma_f32 v[90:91], v[90:91], v[190:191], v[154:155] op_sel_hi:[1,0,1]
	v_lshlrev_b32_e32 v154, 16, v160
	v_mul_f32_e32 v154, v90, v154
	v_and_b32_e32 v155, 0xffff0000, v160
	v_fmac_f32_e32 v154, v91, v155
	v_add_f32_e32 v156, v154, v158
	v_lshlrev_b32_e32 v154, 16, v157
	v_and_b32_e32 v155, 0xffff0000, v157
	v_pk_mul_f32 v[154:155], v[192:193], v[154:155] op_sel_hi:[0,1]
	v_pk_fma_f32 v[92:93], v[92:93], v[190:191], v[154:155] op_sel_hi:[1,0,1]
	v_lshlrev_b32_e32 v154, 16, v161
	v_mul_f32_e32 v154, v92, v154
	v_and_b32_e32 v155, 0xffff0000, v161
	v_fmac_f32_e32 v154, v93, v155
	v_add_f32_e32 v156, v154, v156
	v_lshlrev_b32_e32 v154, 16, v150
	v_and_b32_e32 v155, 0xffff0000, v150
	v_pk_mul_f32 v[154:155], v[192:193], v[154:155] op_sel_hi:[0,1]
	v_pk_fma_f32 v[78:79], v[78:79], v[190:191], v[154:155] op_sel_hi:[1,0,1]
	v_lshlrev_b32_e32 v150, 16, v146
	v_mul_f32_e32 v150, v78, v150
	v_and_b32_e32 v146, 0xffff0000, v146
	v_fmac_f32_e32 v150, v79, v146
	v_add_f32_e32 v146, v150, v156
	v_lshlrev_b32_e32 v150, 16, v151
	v_and_b32_e32 v151, 0xffff0000, v151
	v_pk_mul_f32 v[150:151], v[192:193], v[150:151] op_sel_hi:[0,1]
	v_pk_fma_f32 v[150:151], v[80:81], v[190:191], v[150:151] op_sel_hi:[1,0,1]
	v_lshlrev_b32_e32 v80, 16, v147
	v_mul_f32_e32 v80, v150, v80
	v_and_b32_e32 v81, 0xffff0000, v147
	v_fmac_f32_e32 v80, v151, v81
	v_add_f32_e32 v154, v80, v146
	v_lshlrev_b32_e32 v80, 16, v152
	v_and_b32_e32 v81, 0xffff0000, v152
	v_pk_mul_f32 v[80:81], v[192:193], v[80:81] op_sel_hi:[0,1]
	v_pk_fma_f32 v[146:147], v[74:75], v[190:191], v[80:81] op_sel_hi:[1,0,1]
	v_lshlrev_b32_e32 v74, 16, v148
	v_mul_f32_e32 v74, v146, v74
	v_and_b32_e32 v75, 0xffff0000, v148
	v_fmac_f32_e32 v74, v147, v75
	v_add_f32_e32 v80, v74, v154
	v_lshlrev_b32_e32 v74, 16, v153
	v_and_b32_e32 v75, 0xffff0000, v153
	v_pk_mul_f32 v[74:75], v[192:193], v[74:75] op_sel_hi:[0,1]
	v_pk_fma_f32 v[152:153], v[76:77], v[190:191], v[74:75] op_sel_hi:[1,0,1]
	v_lshlrev_b32_e32 v74, 16, v149
	v_mul_f32_e32 v74, v152, v74
	v_and_b32_e32 v75, 0xffff0000, v149
	v_fmac_f32_e32 v74, v153, v75
	v_add_f32_e32 v74, v74, v80
	s_nop 1
	v_add_f32_dpp v74, v74, v74 quad_perm:[1,0,3,2] row_mask:0xf bank_mask:0xf bound_ctrl:1
	v_readlane_b32 s37, v253, 11
	v_readlane_b32 s38, v253, 12
	v_readlane_b32 s39, v253, 13
	v_readlane_b32 s40, v253, 14
	v_add_f32_dpp v76, v74, v74 quad_perm:[2,3,0,1] row_mask:0xf bank_mask:0xf bound_ctrl:1
	v_readlane_b32 s41, v253, 15
	v_readlane_b32 s42, v253, 16
	v_readlane_b32 s43, v253, 17
	v_readlane_b32 s44, v253, 18
	v_mov_b32_dpp v77, v76 row_half_mirror row_mask:0xf bank_mask:0xf bound_ctrl:1
	v_lshl_add_u64 v[74:75], s[14:15], 2, v[168:169]
	v_readlane_b32 s45, v253, 19
	v_readlane_b32 s46, v253, 20
	v_readlane_b32 s47, v253, 21
	v_readlane_b32 s48, v253, 22
	v_readlane_b32 s49, v253, 23
	s_and_saveexec_b64 s[14:15], s[6:7]
	s_cbranch_execz .LBB0_2450
	s_waitcnt lgkmcnt(0)
	v_add_f32_e32 v80, v76, v77
	s_lshl_b64 s[16:17], s[12:13], 13
	v_fmac_f32_e32 v80, v174, v189
	v_lshl_add_u64 v[76:77], v[74:75], 0, s[16:17]
	global_store_dword v[76:77], v80, off
.LBB0_2450:
	s_or_b64 exec, exec, s[14:15]
	s_waitcnt vmcnt(41)
	v_mul_f32_e32 v76, v187, v173
	v_mul_f32_e32 v76, 0xbfb8aa3b, v76
	v_exp_f32_e32 v154, v76
	s_waitcnt vmcnt(40)
	v_lshlrev_b32_e32 v148, 16, v188
	v_mul_f32_e32 v156, v187, v148
	s_waitcnt vmcnt(39)
	v_lshlrev_b32_e32 v76, 16, v138
	s_waitcnt lgkmcnt(0)
	v_and_b32_e32 v77, 0xffff0000, v138
	v_pk_mul_f32 v[76:77], v[156:157], v[76:77] op_sel_hi:[0,1]
	v_pk_fma_f32 v[76:77], v[102:103], v[154:155], v[76:77] op_sel_hi:[1,0,1]
	s_waitcnt vmcnt(36)
	v_lshlrev_b32_e32 v80, 16, v142
	v_mul_f32_e32 v80, v76, v80
	v_and_b32_e32 v81, 0xffff0000, v142
	v_fmac_f32_e32 v80, v77, v81
	v_add_f32_e32 v102, 0, v80
	v_lshlrev_b32_e32 v80, 16, v139
	v_and_b32_e32 v81, 0xffff0000, v139
	v_pk_mul_f32 v[80:81], v[156:157], v[80:81] op_sel_hi:[0,1]
	v_pk_fma_f32 v[80:81], v[104:105], v[154:155], v[80:81] op_sel_hi:[1,0,1]
	v_lshlrev_b32_e32 v103, 16, v143
	v_mul_f32_e32 v103, v80, v103
	v_and_b32_e32 v104, 0xffff0000, v143
	v_fmac_f32_e32 v103, v81, v104
	v_add_f32_e32 v104, v103, v102
	v_lshlrev_b32_e32 v102, 16, v140
	v_and_b32_e32 v103, 0xffff0000, v140
	v_pk_mul_f32 v[102:103], v[156:157], v[102:103] op_sel_hi:[0,1]
	v_pk_fma_f32 v[90:91], v[90:91], v[154:155], v[102:103] op_sel_hi:[1,0,1]
	v_lshlrev_b32_e32 v102, 16, v144
	v_mul_f32_e32 v102, v90, v102
	v_and_b32_e32 v103, 0xffff0000, v144
	v_fmac_f32_e32 v102, v91, v103
	v_add_f32_e32 v104, v102, v104
	v_lshlrev_b32_e32 v102, 16, v141
	v_and_b32_e32 v103, 0xffff0000, v141
	v_pk_mul_f32 v[102:103], v[156:157], v[102:103] op_sel_hi:[0,1]
	v_pk_fma_f32 v[92:93], v[92:93], v[154:155], v[102:103] op_sel_hi:[1,0,1]
	v_lshlrev_b32_e32 v102, 16, v145
	v_mul_f32_e32 v102, v92, v102
	v_and_b32_e32 v103, 0xffff0000, v145
	v_fmac_f32_e32 v102, v93, v103
	v_add_f32_e32 v104, v102, v104
	v_lshlrev_b32_e32 v102, 16, v134
	v_and_b32_e32 v103, 0xffff0000, v134
	v_pk_mul_f32 v[102:103], v[156:157], v[102:103] op_sel_hi:[0,1]
	v_pk_fma_f32 v[78:79], v[78:79], v[154:155], v[102:103] op_sel_hi:[1,0,1]
	v_lshlrev_b32_e32 v102, 16, v130
	v_mul_f32_e32 v102, v78, v102
	v_and_b32_e32 v103, 0xffff0000, v130
	v_fmac_f32_e32 v102, v79, v103
	v_add_f32_e32 v104, v102, v104
	v_lshlrev_b32_e32 v102, 16, v135
	v_and_b32_e32 v103, 0xffff0000, v135
	v_pk_mul_f32 v[102:103], v[156:157], v[102:103] op_sel_hi:[0,1]
	v_pk_fma_f32 v[102:103], v[150:151], v[154:155], v[102:103] op_sel_hi:[1,0,1]
	v_lshlrev_b32_e32 v105, 16, v131
	v_mul_f32_e32 v105, v102, v105
	v_and_b32_e32 v130, 0xffff0000, v131
	v_fmac_f32_e32 v105, v103, v130
	v_add_f32_e32 v130, v105, v104
	v_lshlrev_b32_e32 v104, 16, v136
	v_and_b32_e32 v105, 0xffff0000, v136
	v_pk_mul_f32 v[104:105], v[156:157], v[104:105] op_sel_hi:[0,1]
	v_pk_fma_f32 v[104:105], v[146:147], v[154:155], v[104:105] op_sel_hi:[1,0,1]
	v_lshlrev_b32_e32 v131, 16, v132
	v_mul_f32_e32 v131, v104, v131
	v_and_b32_e32 v132, 0xffff0000, v132
	v_fmac_f32_e32 v131, v105, v132
	v_add_f32_e32 v132, v131, v130
	v_lshlrev_b32_e32 v130, 16, v137
	v_and_b32_e32 v131, 0xffff0000, v137
	v_pk_mul_f32 v[130:131], v[156:157], v[130:131] op_sel_hi:[0,1]
	v_pk_fma_f32 v[130:131], v[152:153], v[154:155], v[130:131] op_sel_hi:[1,0,1]
	v_lshlrev_b32_e32 v134, 16, v133
	v_mul_f32_e32 v134, v130, v134
	v_and_b32_e32 v133, 0xffff0000, v133
	v_fmac_f32_e32 v134, v131, v133
	v_add_f32_e32 v132, v134, v132
	s_nop 1
	v_add_f32_dpp v132, v132, v132 quad_perm:[1,0,3,2] row_mask:0xf bank_mask:0xf bound_ctrl:1
	s_nop 1
	v_add_f32_dpp v132, v132, v132 quad_perm:[2,3,0,1] row_mask:0xf bank_mask:0xf bound_ctrl:1
	s_nop 1
	v_mov_b32_dpp v133, v132 row_half_mirror row_mask:0xf bank_mask:0xf bound_ctrl:1
	s_and_saveexec_b64 s[14:15], s[6:7]
	s_cbranch_execz .LBB0_2452
	s_lshl_b64 s[16:17], s[12:13], 13
	s_waitcnt lgkmcnt(0)
	v_add_f32_e32 v134, v132, v133
	v_lshl_add_u64 v[132:133], v[74:75], 0, s[16:17]
	v_add_co_u32_e32 v132, vcc, 0x2000, v132
	v_fmac_f32_e32 v134, v174, v148
	s_nop 0
	v_addc_co_u32_e32 v133, vcc, 0, v133, vcc
	global_store_dword v[132:133], v134, off
.LBB0_2452:
	s_or_b64 exec, exec, s[14:15]
	s_waitcnt vmcnt(35)
	v_mul_f32_e32 v132, v185, v173
	v_mul_f32_e32 v132, 0xbfb8aa3b, v132
	v_exp_f32_e32 v134, v132
	s_waitcnt vmcnt(34)
	v_lshlrev_b32_e32 v132, 16, v186
	v_mul_f32_e32 v136, v185, v132
	s_waitcnt vmcnt(33)
	v_lshlrev_b32_e32 v138, 16, v122
	v_and_b32_e32 v139, 0xffff0000, v122
	v_pk_mul_f32 v[138:139], v[136:137], v[138:139] op_sel_hi:[0,1]
	v_pk_fma_f32 v[76:77], v[76:77], v[134:135], v[138:139] op_sel_hi:[1,0,1]
	s_waitcnt vmcnt(30)
	v_lshlrev_b32_e32 v122, 16, v126
	v_mul_f32_e32 v122, v76, v122
	v_and_b32_e32 v126, 0xffff0000, v126
	v_fmac_f32_e32 v122, v77, v126
	v_add_f32_e32 v126, 0, v122
	v_lshlrev_b32_e32 v122, 16, v123
	v_and_b32_e32 v123, 0xffff0000, v123
	v_pk_mul_f32 v[122:123], v[136:137], v[122:123] op_sel_hi:[0,1]
	v_pk_fma_f32 v[80:81], v[80:81], v[134:135], v[122:123] op_sel_hi:[1,0,1]
	v_lshlrev_b32_e32 v122, 16, v127
	v_mul_f32_e32 v122, v80, v122
	v_and_b32_e32 v123, 0xffff0000, v127
	v_fmac_f32_e32 v122, v81, v123
	v_add_f32_e32 v126, v122, v126
	v_lshlrev_b32_e32 v122, 16, v124
	v_and_b32_e32 v123, 0xffff0000, v124
	v_pk_mul_f32 v[122:123], v[136:137], v[122:123] op_sel_hi:[0,1]
	v_pk_fma_f32 v[90:91], v[90:91], v[134:135], v[122:123] op_sel_hi:[1,0,1]
	v_lshlrev_b32_e32 v122, 16, v128
	v_mul_f32_e32 v122, v90, v122
	v_and_b32_e32 v123, 0xffff0000, v128
	v_fmac_f32_e32 v122, v91, v123
	v_add_f32_e32 v124, v122, v126
	v_lshlrev_b32_e32 v122, 16, v125
	v_and_b32_e32 v123, 0xffff0000, v125
	v_pk_mul_f32 v[122:123], v[136:137], v[122:123] op_sel_hi:[0,1]
	v_pk_fma_f32 v[92:93], v[92:93], v[134:135], v[122:123] op_sel_hi:[1,0,1]
	v_lshlrev_b32_e32 v122, 16, v129
	v_mul_f32_e32 v122, v92, v122
	v_and_b32_e32 v123, 0xffff0000, v129
	v_fmac_f32_e32 v122, v93, v123
	v_add_f32_e32 v124, v122, v124
	v_lshlrev_b32_e32 v122, 16, v118
	v_and_b32_e32 v123, 0xffff0000, v118
	v_pk_mul_f32 v[122:123], v[136:137], v[122:123] op_sel_hi:[0,1]
	v_pk_fma_f32 v[78:79], v[78:79], v[134:135], v[122:123] op_sel_hi:[1,0,1]
	v_lshlrev_b32_e32 v118, 16, v114
	v_mul_f32_e32 v118, v78, v118
	v_and_b32_e32 v114, 0xffff0000, v114
	v_fmac_f32_e32 v118, v79, v114
	v_add_f32_e32 v114, v118, v124
	v_lshlrev_b32_e32 v118, 16, v119
	v_and_b32_e32 v119, 0xffff0000, v119
	v_pk_mul_f32 v[118:119], v[136:137], v[118:119] op_sel_hi:[0,1]
	v_pk_fma_f32 v[102:103], v[102:103], v[134:135], v[118:119] op_sel_hi:[1,0,1]
	v_lshlrev_b32_e32 v118, 16, v115
	v_mul_f32_e32 v118, v102, v118
	v_and_b32_e32 v115, 0xffff0000, v115
	v_fmac_f32_e32 v118, v103, v115
	v_add_f32_e32 v118, v118, v114
	v_lshlrev_b32_e32 v114, 16, v120
	v_and_b32_e32 v115, 0xffff0000, v120
	v_pk_mul_f32 v[114:115], v[136:137], v[114:115] op_sel_hi:[0,1]
	v_pk_fma_f32 v[104:105], v[104:105], v[134:135], v[114:115] op_sel_hi:[1,0,1]
	v_lshlrev_b32_e32 v114, 16, v116
	v_mul_f32_e32 v114, v104, v114
	v_and_b32_e32 v115, 0xffff0000, v116
	v_fmac_f32_e32 v114, v105, v115
	v_add_f32_e32 v116, v114, v118
	v_lshlrev_b32_e32 v114, 16, v121
	v_and_b32_e32 v115, 0xffff0000, v121
	v_pk_mul_f32 v[114:115], v[136:137], v[114:115] op_sel_hi:[0,1]
	v_pk_fma_f32 v[114:115], v[130:131], v[134:135], v[114:115] op_sel_hi:[1,0,1]
	v_lshlrev_b32_e32 v118, 16, v117
	v_mul_f32_e32 v118, v114, v118
	v_and_b32_e32 v117, 0xffff0000, v117
	v_fmac_f32_e32 v118, v115, v117
	v_add_f32_e32 v116, v118, v116
	s_nop 1
	v_add_f32_dpp v116, v116, v116 quad_perm:[1,0,3,2] row_mask:0xf bank_mask:0xf bound_ctrl:1
	s_nop 1
	v_add_f32_dpp v116, v116, v116 quad_perm:[2,3,0,1] row_mask:0xf bank_mask:0xf bound_ctrl:1
	s_nop 1
	v_mov_b32_dpp v117, v116 row_half_mirror row_mask:0xf bank_mask:0xf bound_ctrl:1
	s_and_saveexec_b64 s[14:15], s[6:7]
	s_cbranch_execz .LBB0_2454
	s_lshl_b64 s[16:17], s[12:13], 13
	s_waitcnt lgkmcnt(0)
	v_add_f32_e32 v118, v116, v117
	v_lshl_add_u64 v[116:117], v[74:75], 0, s[16:17]
	v_add_co_u32_e32 v116, vcc, 0x4000, v116
	v_fmac_f32_e32 v118, v174, v132
	s_nop 0
	v_addc_co_u32_e32 v117, vcc, 0, v117, vcc
	global_store_dword v[116:117], v118, off
.LBB0_2454:
	s_or_b64 exec, exec, s[14:15]
	s_waitcnt vmcnt(29)
	v_mul_f32_e32 v116, v183, v173
	v_mul_f32_e32 v116, 0xbfb8aa3b, v116
	v_exp_f32_e32 v118, v116
	s_waitcnt vmcnt(28)
	v_lshlrev_b32_e32 v116, 16, v184
	v_mul_f32_e32 v120, v183, v116
	s_waitcnt vmcnt(27)
	v_lshlrev_b32_e32 v122, 16, v106
	v_and_b32_e32 v123, 0xffff0000, v106
	v_pk_mul_f32 v[122:123], v[120:121], v[122:123] op_sel_hi:[0,1]
	v_pk_fma_f32 v[76:77], v[76:77], v[118:119], v[122:123] op_sel_hi:[1,0,1]
	s_waitcnt vmcnt(24)
	v_lshlrev_b32_e32 v106, 16, v110
	v_mul_f32_e32 v106, v76, v106
	v_and_b32_e32 v110, 0xffff0000, v110
	v_fmac_f32_e32 v106, v77, v110
	v_add_f32_e32 v110, 0, v106
	v_lshlrev_b32_e32 v106, 16, v107
	v_and_b32_e32 v107, 0xffff0000, v107
	v_pk_mul_f32 v[106:107], v[120:121], v[106:107] op_sel_hi:[0,1]
	v_pk_fma_f32 v[80:81], v[80:81], v[118:119], v[106:107] op_sel_hi:[1,0,1]
	v_lshlrev_b32_e32 v106, 16, v111
	v_mul_f32_e32 v106, v80, v106
	v_and_b32_e32 v107, 0xffff0000, v111
	v_fmac_f32_e32 v106, v81, v107
	v_add_f32_e32 v110, v106, v110
	v_lshlrev_b32_e32 v106, 16, v108
	v_and_b32_e32 v107, 0xffff0000, v108
	v_pk_mul_f32 v[106:107], v[120:121], v[106:107] op_sel_hi:[0,1]
	v_pk_fma_f32 v[90:91], v[90:91], v[118:119], v[106:107] op_sel_hi:[1,0,1]
	v_lshlrev_b32_e32 v106, 16, v112
	v_mul_f32_e32 v106, v90, v106
	v_and_b32_e32 v107, 0xffff0000, v112
	v_fmac_f32_e32 v106, v91, v107
	v_add_f32_e32 v108, v106, v110
	v_lshlrev_b32_e32 v106, 16, v109
	v_and_b32_e32 v107, 0xffff0000, v109
	v_pk_mul_f32 v[106:107], v[120:121], v[106:107] op_sel_hi:[0,1]
	v_pk_fma_f32 v[92:93], v[92:93], v[118:119], v[106:107] op_sel_hi:[1,0,1]
	v_lshlrev_b32_e32 v106, 16, v113
	v_mul_f32_e32 v106, v92, v106
	v_and_b32_e32 v107, 0xffff0000, v113
	v_fmac_f32_e32 v106, v93, v107
	v_add_f32_e32 v108, v106, v108
	v_lshlrev_b32_e32 v106, 16, v98
	v_and_b32_e32 v107, 0xffff0000, v98
	v_pk_mul_f32 v[106:107], v[120:121], v[106:107] op_sel_hi:[0,1]
	v_pk_fma_f32 v[78:79], v[78:79], v[118:119], v[106:107] op_sel_hi:[1,0,1]
	v_lshlrev_b32_e32 v98, 16, v94
	v_mul_f32_e32 v98, v78, v98
	v_and_b32_e32 v94, 0xffff0000, v94
	v_fmac_f32_e32 v98, v79, v94
	v_add_f32_e32 v94, v98, v108
	v_lshlrev_b32_e32 v98, 16, v99
	v_and_b32_e32 v99, 0xffff0000, v99
	v_pk_mul_f32 v[98:99], v[120:121], v[98:99] op_sel_hi:[0,1]
	v_pk_fma_f32 v[98:99], v[102:103], v[118:119], v[98:99] op_sel_hi:[1,0,1]
	v_lshlrev_b32_e32 v102, 16, v95
	v_mul_f32_e32 v102, v98, v102
	v_and_b32_e32 v95, 0xffff0000, v95
	v_fmac_f32_e32 v102, v99, v95
	v_add_f32_e32 v102, v102, v94
	v_lshlrev_b32_e32 v94, 16, v100
	v_and_b32_e32 v95, 0xffff0000, v100
	v_pk_mul_f32 v[94:95], v[120:121], v[94:95] op_sel_hi:[0,1]
	v_pk_fma_f32 v[94:95], v[104:105], v[118:119], v[94:95] op_sel_hi:[1,0,1]
	v_lshlrev_b32_e32 v100, 16, v96
	v_mul_f32_e32 v100, v94, v100
	v_and_b32_e32 v96, 0xffff0000, v96
	v_fmac_f32_e32 v100, v95, v96
	v_add_f32_e32 v96, v100, v102
	v_lshlrev_b32_e32 v100, 16, v101
	v_and_b32_e32 v101, 0xffff0000, v101
	v_pk_mul_f32 v[100:101], v[120:121], v[100:101] op_sel_hi:[0,1]
	v_pk_fma_f32 v[100:101], v[114:115], v[118:119], v[100:101] op_sel_hi:[1,0,1]
	v_lshlrev_b32_e32 v102, 16, v97
	v_mul_f32_e32 v102, v100, v102
	v_and_b32_e32 v97, 0xffff0000, v97
	v_fmac_f32_e32 v102, v101, v97
	v_add_f32_e32 v96, v102, v96
	s_nop 1
	v_add_f32_dpp v96, v96, v96 quad_perm:[1,0,3,2] row_mask:0xf bank_mask:0xf bound_ctrl:1
	s_nop 1
	v_add_f32_dpp v96, v96, v96 quad_perm:[2,3,0,1] row_mask:0xf bank_mask:0xf bound_ctrl:1
	s_nop 1
	v_mov_b32_dpp v97, v96 row_half_mirror row_mask:0xf bank_mask:0xf bound_ctrl:1
	s_and_saveexec_b64 s[14:15], s[6:7]
	s_cbranch_execz .LBB0_2456
	s_lshl_b64 s[16:17], s[12:13], 13
	s_waitcnt lgkmcnt(0)
	v_add_f32_e32 v102, v96, v97
	v_lshl_add_u64 v[96:97], v[74:75], 0, s[16:17]
	v_add_co_u32_e32 v96, vcc, 0x6000, v96
	v_fmac_f32_e32 v102, v174, v116
	s_nop 0
	v_addc_co_u32_e32 v97, vcc, 0, v97, vcc
	global_store_dword v[96:97], v102, off
.LBB0_2456:
	s_or_b64 exec, exec, s[14:15]
	s_waitcnt vmcnt(23)
	v_mul_f32_e32 v96, v181, v173
	v_mul_f32_e32 v96, 0xbfb8aa3b, v96
	v_exp_f32_e32 v102, v96
	s_waitcnt vmcnt(22)
	v_lshlrev_b32_e32 v96, 16, v182
	v_mul_f32_e32 v104, v181, v96
	s_waitcnt vmcnt(21)
	v_lshlrev_b32_e32 v106, 16, v82
	v_and_b32_e32 v107, 0xffff0000, v82
	v_pk_mul_f32 v[106:107], v[104:105], v[106:107] op_sel_hi:[0,1]
	v_pk_fma_f32 v[76:77], v[76:77], v[102:103], v[106:107] op_sel_hi:[1,0,1]
	s_waitcnt vmcnt(18)
	v_lshlrev_b32_e32 v82, 16, v86
	v_mul_f32_e32 v82, v76, v82
	v_and_b32_e32 v86, 0xffff0000, v86
	v_fmac_f32_e32 v82, v77, v86
	v_add_f32_e32 v86, 0, v82
	v_lshlrev_b32_e32 v82, 16, v83
	v_and_b32_e32 v83, 0xffff0000, v83
	v_pk_mul_f32 v[82:83], v[104:105], v[82:83] op_sel_hi:[0,1]
	v_pk_fma_f32 v[80:81], v[80:81], v[102:103], v[82:83] op_sel_hi:[1,0,1]
	v_lshlrev_b32_e32 v82, 16, v87
	v_mul_f32_e32 v82, v80, v82
	v_and_b32_e32 v83, 0xffff0000, v87
	v_fmac_f32_e32 v82, v81, v83
	v_add_f32_e32 v86, v82, v86
	v_lshlrev_b32_e32 v82, 16, v84
	v_and_b32_e32 v83, 0xffff0000, v84
	v_pk_mul_f32 v[82:83], v[104:105], v[82:83] op_sel_hi:[0,1]
	v_pk_fma_f32 v[82:83], v[90:91], v[102:103], v[82:83] op_sel_hi:[1,0,1]
	v_lshlrev_b32_e32 v84, 16, v88
	v_mul_f32_e32 v84, v82, v84
	v_and_b32_e32 v87, 0xffff0000, v88
	v_fmac_f32_e32 v84, v83, v87
	v_add_f32_e32 v86, v84, v86
	v_lshlrev_b32_e32 v84, 16, v85
	v_and_b32_e32 v85, 0xffff0000, v85
	v_pk_mul_f32 v[84:85], v[104:105], v[84:85] op_sel_hi:[0,1]
	v_pk_fma_f32 v[84:85], v[92:93], v[102:103], v[84:85] op_sel_hi:[1,0,1]
	v_lshlrev_b32_e32 v87, 16, v89
	v_mul_f32_e32 v87, v84, v87
	v_and_b32_e32 v88, 0xffff0000, v89
	v_fmac_f32_e32 v87, v85, v88
	v_add_f32_e32 v88, v87, v86
	v_lshlrev_b32_e32 v86, 16, v70
	v_and_b32_e32 v87, 0xffff0000, v70
	v_pk_mul_f32 v[86:87], v[104:105], v[86:87] op_sel_hi:[0,1]
	v_pk_fma_f32 v[78:79], v[78:79], v[102:103], v[86:87] op_sel_hi:[1,0,1]
	v_lshlrev_b32_e32 v70, 16, v66
	v_mul_f32_e32 v70, v78, v70
	v_and_b32_e32 v66, 0xffff0000, v66
	v_fmac_f32_e32 v70, v79, v66
	v_add_f32_e32 v66, v70, v88
	v_lshlrev_b32_e32 v70, 16, v71
	v_and_b32_e32 v71, 0xffff0000, v71
	v_pk_mul_f32 v[70:71], v[104:105], v[70:71] op_sel_hi:[0,1]
	v_pk_fma_f32 v[70:71], v[98:99], v[102:103], v[70:71] op_sel_hi:[1,0,1]
	v_lshlrev_b32_e32 v86, 16, v67
	v_mul_f32_e32 v86, v70, v86
	v_and_b32_e32 v67, 0xffff0000, v67
	v_fmac_f32_e32 v86, v71, v67
	v_add_f32_e32 v86, v86, v66
	v_lshlrev_b32_e32 v66, 16, v72
	v_and_b32_e32 v67, 0xffff0000, v72
	v_pk_mul_f32 v[66:67], v[104:105], v[66:67] op_sel_hi:[0,1]
	v_pk_fma_f32 v[66:67], v[94:95], v[102:103], v[66:67] op_sel_hi:[1,0,1]
	v_lshlrev_b32_e32 v72, 16, v68
	v_mul_f32_e32 v72, v66, v72
	v_and_b32_e32 v68, 0xffff0000, v68
	v_fmac_f32_e32 v72, v67, v68
	v_add_f32_e32 v68, v72, v86
	v_lshlrev_b32_e32 v72, 16, v73
	v_and_b32_e32 v73, 0xffff0000, v73
	v_pk_mul_f32 v[72:73], v[104:105], v[72:73] op_sel_hi:[0,1]
	v_pk_fma_f32 v[72:73], v[100:101], v[102:103], v[72:73] op_sel_hi:[1,0,1]
	v_lshlrev_b32_e32 v86, 16, v69
	v_mul_f32_e32 v86, v72, v86
	v_and_b32_e32 v69, 0xffff0000, v69
	v_fmac_f32_e32 v86, v73, v69
	v_add_f32_e32 v68, v86, v68
	s_nop 1
	v_add_f32_dpp v68, v68, v68 quad_perm:[1,0,3,2] row_mask:0xf bank_mask:0xf bound_ctrl:1
	s_nop 1
	v_add_f32_dpp v68, v68, v68 quad_perm:[2,3,0,1] row_mask:0xf bank_mask:0xf bound_ctrl:1
	s_nop 1
	v_mov_b32_dpp v69, v68 row_half_mirror row_mask:0xf bank_mask:0xf bound_ctrl:1
	s_and_saveexec_b64 s[14:15], s[6:7]
	s_cbranch_execz .LBB0_2458
	s_lshl_b64 s[16:17], s[12:13], 13
	s_waitcnt lgkmcnt(0)
	v_add_f32_e32 v86, v68, v69
	v_lshl_add_u64 v[68:69], v[74:75], 0, s[16:17]
	v_add_co_u32_e32 v68, vcc, 0x8000, v68
	v_fmac_f32_e32 v86, v174, v96
	s_nop 0
	v_addc_co_u32_e32 v69, vcc, 0, v69, vcc
	global_store_dword v[68:69], v86, off
.LBB0_2458:
	s_or_b64 exec, exec, s[14:15]
	s_waitcnt vmcnt(17)
	v_mul_f32_e32 v68, v179, v173
	v_mul_f32_e32 v68, 0xbfb8aa3b, v68
	v_exp_f32_e32 v88, v68
	s_waitcnt vmcnt(16)
	v_lshlrev_b32_e32 v86, 16, v180
	v_mul_f32_e32 v90, v179, v86
	s_waitcnt vmcnt(15)
	v_lshlrev_b32_e32 v68, 16, v58
	s_waitcnt lgkmcnt(0)
	v_and_b32_e32 v69, 0xffff0000, v58
	v_pk_mul_f32 v[68:69], v[90:91], v[68:69] op_sel_hi:[0,1]
	v_pk_fma_f32 v[68:69], v[76:77], v[88:89], v[68:69] op_sel_hi:[1,0,1]
	s_waitcnt vmcnt(12)
	v_lshlrev_b32_e32 v58, 16, v62
	v_mul_f32_e32 v58, v68, v58
	v_and_b32_e32 v62, 0xffff0000, v62
	v_fmac_f32_e32 v58, v69, v62
	v_add_f32_e32 v62, 0, v58
	v_lshlrev_b32_e32 v58, 16, v59
	v_and_b32_e32 v59, 0xffff0000, v59
	v_pk_mul_f32 v[58:59], v[90:91], v[58:59] op_sel_hi:[0,1]
	v_pk_fma_f32 v[58:59], v[80:81], v[88:89], v[58:59] op_sel_hi:[1,0,1]
	v_lshlrev_b32_e32 v76, 16, v63
	v_mul_f32_e32 v76, v58, v76
	v_and_b32_e32 v63, 0xffff0000, v63
	v_fmac_f32_e32 v76, v59, v63
	v_add_f32_e32 v76, v76, v62
	v_lshlrev_b32_e32 v62, 16, v60
	v_and_b32_e32 v63, 0xffff0000, v60
	v_pk_mul_f32 v[62:63], v[90:91], v[62:63] op_sel_hi:[0,1]
	v_pk_fma_f32 v[62:63], v[82:83], v[88:89], v[62:63] op_sel_hi:[1,0,1]
	v_lshlrev_b32_e32 v60, 16, v64
	v_mul_f32_e32 v60, v62, v60
	v_and_b32_e32 v64, 0xffff0000, v64
	v_fmac_f32_e32 v60, v63, v64
	v_add_f32_e32 v64, v60, v76
	v_lshlrev_b32_e32 v60, 16, v61
	v_and_b32_e32 v61, 0xffff0000, v61
	v_pk_mul_f32 v[60:61], v[90:91], v[60:61] op_sel_hi:[0,1]
	v_pk_fma_f32 v[60:61], v[84:85], v[88:89], v[60:61] op_sel_hi:[1,0,1]
	v_lshlrev_b32_e32 v76, 16, v65
	v_mul_f32_e32 v76, v60, v76
	v_and_b32_e32 v65, 0xffff0000, v65
	v_fmac_f32_e32 v76, v61, v65
	v_add_f32_e32 v76, v76, v64
	v_lshlrev_b32_e32 v64, 16, v50
	v_and_b32_e32 v65, 0xffff0000, v50
	v_pk_mul_f32 v[64:65], v[90:91], v[64:65] op_sel_hi:[0,1]
	v_pk_fma_f32 v[64:65], v[78:79], v[88:89], v[64:65] op_sel_hi:[1,0,1]
	v_lshlrev_b32_e32 v50, 16, v54
	v_mul_f32_e32 v50, v64, v50
	v_and_b32_e32 v54, 0xffff0000, v54
	v_fmac_f32_e32 v50, v65, v54
	v_add_f32_e32 v54, v50, v76
	v_lshlrev_b32_e32 v50, 16, v51
	v_and_b32_e32 v51, 0xffff0000, v51
	v_pk_mul_f32 v[50:51], v[90:91], v[50:51] op_sel_hi:[0,1]
	v_pk_fma_f32 v[50:51], v[70:71], v[88:89], v[50:51] op_sel_hi:[1,0,1]
	v_lshlrev_b32_e32 v70, 16, v55
	v_mul_f32_e32 v70, v50, v70
	v_and_b32_e32 v55, 0xffff0000, v55
	v_fmac_f32_e32 v70, v51, v55
	v_add_f32_e32 v70, v70, v54
	v_lshlrev_b32_e32 v54, 16, v52
	v_and_b32_e32 v55, 0xffff0000, v52
	v_pk_mul_f32 v[54:55], v[90:91], v[54:55] op_sel_hi:[0,1]
	v_pk_fma_f32 v[54:55], v[66:67], v[88:89], v[54:55] op_sel_hi:[1,0,1]
	v_lshlrev_b32_e32 v52, 16, v56
	v_mul_f32_e32 v52, v54, v52
	v_and_b32_e32 v56, 0xffff0000, v56
	v_fmac_f32_e32 v52, v55, v56
	v_add_f32_e32 v56, v52, v70
	v_lshlrev_b32_e32 v52, 16, v53
	v_and_b32_e32 v53, 0xffff0000, v53
	v_pk_mul_f32 v[52:53], v[90:91], v[52:53] op_sel_hi:[0,1]
	v_pk_fma_f32 v[52:53], v[72:73], v[88:89], v[52:53] op_sel_hi:[1,0,1]
	v_lshlrev_b32_e32 v66, 16, v57
	v_mul_f32_e32 v66, v52, v66
	v_and_b32_e32 v57, 0xffff0000, v57
	v_fmac_f32_e32 v66, v53, v57
	v_add_f32_e32 v56, v66, v56
	s_nop 1
	v_add_f32_dpp v56, v56, v56 quad_perm:[1,0,3,2] row_mask:0xf bank_mask:0xf bound_ctrl:1
	s_nop 1
	v_add_f32_dpp v56, v56, v56 quad_perm:[2,3,0,1] row_mask:0xf bank_mask:0xf bound_ctrl:1
	s_nop 1
	v_mov_b32_dpp v57, v56 row_half_mirror row_mask:0xf bank_mask:0xf bound_ctrl:1
	s_and_saveexec_b64 s[14:15], s[6:7]
	s_cbranch_execz .LBB0_2460
	s_lshl_b64 s[16:17], s[12:13], 13
	s_waitcnt lgkmcnt(0)
	v_add_f32_e32 v66, v56, v57
	v_lshl_add_u64 v[56:57], v[74:75], 0, s[16:17]
	v_add_co_u32_e32 v56, vcc, 0xa000, v56
	v_fmac_f32_e32 v66, v174, v86
	s_nop 0
	v_addc_co_u32_e32 v57, vcc, 0, v57, vcc
	global_store_dword v[56:57], v66, off
.LBB0_2460:
	s_or_b64 exec, exec, s[14:15]
	s_waitcnt vmcnt(11)
	v_mul_f32_e32 v56, v177, v173
	v_mul_f32_e32 v56, 0xbfb8aa3b, v56
	v_exp_f32_e32 v70, v56
	s_waitcnt vmcnt(10)
	v_lshlrev_b32_e32 v66, 16, v178
	v_mul_f32_e32 v72, v177, v66
	s_waitcnt vmcnt(9)
	v_lshlrev_b32_e32 v56, 16, v42
	s_waitcnt lgkmcnt(0)
	v_and_b32_e32 v57, 0xffff0000, v42
	v_pk_mul_f32 v[56:57], v[72:73], v[56:57] op_sel_hi:[0,1]
	v_pk_fma_f32 v[56:57], v[68:69], v[70:71], v[56:57] op_sel_hi:[1,0,1]
	s_waitcnt vmcnt(6)
	v_lshlrev_b32_e32 v42, 16, v46
	v_mul_f32_e32 v42, v56, v42
	v_and_b32_e32 v46, 0xffff0000, v46
	v_fmac_f32_e32 v42, v57, v46
	v_add_f32_e32 v46, 0, v42
	v_lshlrev_b32_e32 v42, 16, v43
	v_and_b32_e32 v43, 0xffff0000, v43
	v_pk_mul_f32 v[42:43], v[72:73], v[42:43] op_sel_hi:[0,1]
	v_pk_fma_f32 v[42:43], v[58:59], v[70:71], v[42:43] op_sel_hi:[1,0,1]
	v_lshlrev_b32_e32 v58, 16, v47
	v_mul_f32_e32 v58, v42, v58
	v_and_b32_e32 v47, 0xffff0000, v47
	v_fmac_f32_e32 v58, v43, v47
	v_add_f32_e32 v58, v58, v46
	v_lshlrev_b32_e32 v46, 16, v44
	v_and_b32_e32 v47, 0xffff0000, v44
	v_pk_mul_f32 v[46:47], v[72:73], v[46:47] op_sel_hi:[0,1]
	v_pk_fma_f32 v[46:47], v[62:63], v[70:71], v[46:47] op_sel_hi:[1,0,1]
	v_lshlrev_b32_e32 v44, 16, v48
	v_mul_f32_e32 v44, v46, v44
	v_and_b32_e32 v48, 0xffff0000, v48
	v_fmac_f32_e32 v44, v47, v48
	v_add_f32_e32 v48, v44, v58
	v_lshlrev_b32_e32 v44, 16, v45
	v_and_b32_e32 v45, 0xffff0000, v45
	v_pk_mul_f32 v[44:45], v[72:73], v[44:45] op_sel_hi:[0,1]
	v_pk_fma_f32 v[44:45], v[60:61], v[70:71], v[44:45] op_sel_hi:[1,0,1]
	v_lshlrev_b32_e32 v58, 16, v49
	v_mul_f32_e32 v58, v44, v58
	v_and_b32_e32 v49, 0xffff0000, v49
	v_fmac_f32_e32 v58, v45, v49
	v_add_f32_e32 v58, v58, v48
	v_lshlrev_b32_e32 v48, 16, v34
	v_and_b32_e32 v49, 0xffff0000, v34
	v_pk_mul_f32 v[48:49], v[72:73], v[48:49] op_sel_hi:[0,1]
	v_pk_fma_f32 v[48:49], v[64:65], v[70:71], v[48:49] op_sel_hi:[1,0,1]
	v_lshlrev_b32_e32 v34, 16, v38
	v_mul_f32_e32 v34, v48, v34
	v_and_b32_e32 v38, 0xffff0000, v38
	v_fmac_f32_e32 v34, v49, v38
	v_add_f32_e32 v38, v34, v58
	v_lshlrev_b32_e32 v34, 16, v35
	v_and_b32_e32 v35, 0xffff0000, v35
	v_pk_mul_f32 v[34:35], v[72:73], v[34:35] op_sel_hi:[0,1]
	v_pk_fma_f32 v[50:51], v[50:51], v[70:71], v[34:35] op_sel_hi:[1,0,1]
	v_lshlrev_b32_e32 v34, 16, v39
	v_mul_f32_e32 v34, v50, v34
	v_and_b32_e32 v35, 0xffff0000, v39
	v_fmac_f32_e32 v34, v51, v35
	v_add_f32_e32 v58, v34, v38
	v_lshlrev_b32_e32 v34, 16, v36
	v_and_b32_e32 v35, 0xffff0000, v36
	v_pk_mul_f32 v[34:35], v[72:73], v[34:35] op_sel_hi:[0,1]
	v_pk_fma_f32 v[38:39], v[54:55], v[70:71], v[34:35] op_sel_hi:[1,0,1]
	v_lshlrev_b32_e32 v34, 16, v40
	v_mul_f32_e32 v34, v38, v34
	v_and_b32_e32 v35, 0xffff0000, v40
	v_fmac_f32_e32 v34, v39, v35
	v_add_f32_e32 v36, v34, v58
	v_lshlrev_b32_e32 v34, 16, v37
	v_and_b32_e32 v35, 0xffff0000, v37
	v_pk_mul_f32 v[34:35], v[72:73], v[34:35] op_sel_hi:[0,1]
	v_pk_fma_f32 v[52:53], v[52:53], v[70:71], v[34:35] op_sel_hi:[1,0,1]
	v_lshlrev_b32_e32 v34, 16, v41
	v_mul_f32_e32 v34, v52, v34
	v_and_b32_e32 v35, 0xffff0000, v41
	v_fmac_f32_e32 v34, v53, v35
	v_add_f32_e32 v34, v34, v36
	s_nop 1
	v_add_f32_dpp v34, v34, v34 quad_perm:[1,0,3,2] row_mask:0xf bank_mask:0xf bound_ctrl:1
	s_nop 1
	v_add_f32_dpp v34, v34, v34 quad_perm:[2,3,0,1] row_mask:0xf bank_mask:0xf bound_ctrl:1
	s_nop 1
	v_mov_b32_dpp v35, v34 row_half_mirror row_mask:0xf bank_mask:0xf bound_ctrl:1
	s_and_saveexec_b64 s[14:15], s[6:7]
	s_cbranch_execz .LBB0_2462
	s_lshl_b64 s[16:17], s[12:13], 13
	s_waitcnt lgkmcnt(0)
	v_add_f32_e32 v36, v34, v35
	v_lshl_add_u64 v[34:35], v[74:75], 0, s[16:17]
	v_add_co_u32_e32 v34, vcc, 0xc000, v34
	v_fmac_f32_e32 v36, v174, v66
	s_nop 0
	v_addc_co_u32_e32 v35, vcc, 0, v35, vcc
	global_store_dword v[34:35], v36, off
.LBB0_2462:
	s_or_b64 exec, exec, s[14:15]
	s_waitcnt vmcnt(5)
	v_mul_f32_e32 v34, v175, v173
	v_mul_f32_e32 v34, 0xbfb8aa3b, v34
	v_exp_f32_e32 v54, v34
	s_waitcnt vmcnt(4)
	v_lshlrev_b32_e32 v40, 16, v176
	v_mul_f32_e32 v58, v175, v40
	s_waitcnt vmcnt(3)
	v_lshlrev_b32_e32 v34, 16, v26
	s_waitcnt lgkmcnt(0)
	v_and_b32_e32 v35, 0xffff0000, v26
	v_pk_mul_f32 v[34:35], v[58:59], v[34:35] op_sel_hi:[0,1]
	v_pk_fma_f32 v[34:35], v[56:57], v[54:55], v[34:35] op_sel_hi:[1,0,1]
	s_waitcnt vmcnt(0)
	v_lshlrev_b32_e32 v26, 16, v30
	v_mul_f32_e32 v26, v34, v26
	v_and_b32_e32 v30, 0xffff0000, v30
	v_fmac_f32_e32 v26, v35, v30
	v_add_f32_e32 v30, 0, v26
	v_lshlrev_b32_e32 v26, 16, v27
	v_and_b32_e32 v27, 0xffff0000, v27
	v_pk_mul_f32 v[26:27], v[58:59], v[26:27] op_sel_hi:[0,1]
	v_pk_fma_f32 v[36:37], v[42:43], v[54:55], v[26:27] op_sel_hi:[1,0,1]
	v_lshlrev_b32_e32 v26, 16, v31
	v_mul_f32_e32 v26, v36, v26
	v_and_b32_e32 v27, 0xffff0000, v31
	v_fmac_f32_e32 v26, v37, v27
	v_add_f32_e32 v30, v26, v30
	v_lshlrev_b32_e32 v26, 16, v28
	v_and_b32_e32 v27, 0xffff0000, v28
	v_pk_mul_f32 v[26:27], v[58:59], v[26:27] op_sel_hi:[0,1]
	v_pk_fma_f32 v[26:27], v[46:47], v[54:55], v[26:27] op_sel_hi:[1,0,1]
	v_lshlrev_b32_e32 v28, 16, v32
	v_mul_f32_e32 v28, v26, v28
	v_and_b32_e32 v31, 0xffff0000, v32
	v_fmac_f32_e32 v28, v27, v31
	v_add_f32_e32 v30, v28, v30
	v_lshlrev_b32_e32 v28, 16, v29
	v_and_b32_e32 v29, 0xffff0000, v29
	v_pk_mul_f32 v[28:29], v[58:59], v[28:29] op_sel_hi:[0,1]
	v_pk_fma_f32 v[28:29], v[44:45], v[54:55], v[28:29] op_sel_hi:[1,0,1]
	v_lshlrev_b32_e32 v31, 16, v33
	v_mul_f32_e32 v31, v28, v31
	v_and_b32_e32 v32, 0xffff0000, v33
	v_fmac_f32_e32 v31, v29, v32
	v_add_f32_e32 v32, v31, v30
	v_lshlrev_b32_e32 v30, 16, v22
	v_and_b32_e32 v31, 0xffff0000, v22
	v_pk_mul_f32 v[30:31], v[58:59], v[30:31] op_sel_hi:[0,1]
	v_pk_fma_f32 v[30:31], v[48:49], v[54:55], v[30:31] op_sel_hi:[1,0,1]
	v_lshlrev_b32_e32 v22, 16, v18
	v_mul_f32_e32 v22, v30, v22
	v_and_b32_e32 v18, 0xffff0000, v18
	v_fmac_f32_e32 v22, v31, v18
	v_add_f32_e32 v18, v22, v32
	v_lshlrev_b32_e32 v22, 16, v23
	v_and_b32_e32 v23, 0xffff0000, v23
	v_pk_mul_f32 v[22:23], v[58:59], v[22:23] op_sel_hi:[0,1]
	v_pk_fma_f32 v[32:33], v[50:51], v[54:55], v[22:23] op_sel_hi:[1,0,1]
	v_lshlrev_b32_e32 v22, 16, v19
	v_mul_f32_e32 v22, v32, v22
	v_and_b32_e32 v19, 0xffff0000, v19
	v_fmac_f32_e32 v22, v33, v19
	v_add_f32_e32 v41, v22, v18
	v_lshlrev_b32_e32 v18, 16, v24
	v_and_b32_e32 v19, 0xffff0000, v24
	v_pk_mul_f32 v[18:19], v[58:59], v[18:19] op_sel_hi:[0,1]
	v_pk_fma_f32 v[22:23], v[38:39], v[54:55], v[18:19] op_sel_hi:[1,0,1]
	v_lshlrev_b32_e32 v18, 16, v20
	v_mul_f32_e32 v18, v22, v18
	v_and_b32_e32 v19, 0xffff0000, v20
	v_fmac_f32_e32 v18, v23, v19
	v_add_f32_e32 v20, v18, v41
	v_lshlrev_b32_e32 v18, 16, v25
	v_and_b32_e32 v19, 0xffff0000, v25
	v_pk_mul_f32 v[18:19], v[58:59], v[18:19] op_sel_hi:[0,1]
	v_pk_fma_f32 v[24:25], v[52:53], v[54:55], v[18:19] op_sel_hi:[1,0,1]
	v_lshlrev_b32_e32 v18, 16, v21
	v_mul_f32_e32 v18, v24, v18
	v_and_b32_e32 v19, 0xffff0000, v21
	v_fmac_f32_e32 v18, v25, v19
	v_add_f32_e32 v18, v18, v20
	s_nop 1
	v_add_f32_dpp v18, v18, v18 quad_perm:[1,0,3,2] row_mask:0xf bank_mask:0xf bound_ctrl:1
	s_nop 1
	v_add_f32_dpp v18, v18, v18 quad_perm:[2,3,0,1] row_mask:0xf bank_mask:0xf bound_ctrl:1
	s_nop 1
	v_mov_b32_dpp v19, v18 row_half_mirror row_mask:0xf bank_mask:0xf bound_ctrl:1
	s_and_saveexec_b64 s[14:15], s[6:7]
	s_cbranch_execz .LBB0_2445
	s_lshl_b64 s[12:13], s[12:13], 13
	s_waitcnt lgkmcnt(0)
	v_add_f32_e32 v20, v18, v19
	v_lshl_add_u64 v[18:19], v[74:75], 0, s[12:13]
	v_add_co_u32_e32 v18, vcc, 0xe000, v18
	v_fmac_f32_e32 v20, v174, v40
	s_nop 0
	v_addc_co_u32_e32 v19, vcc, 0, v19, vcc
	global_store_dword v[18:19], v20, off
	s_branch .LBB0_2445
